# E25: E14 + GEMM accumulator zeroing with 64-bit moves (127 v_mov_b32 -> 63 v_mov_b64 + 1 per tile, 4 GEMM phases)
# speedup vs baseline: 1.0002x; 1.0002x over previous
; template <class Epi>
; __device__ __forceinline__ void gemm_phase(LAS unsigned char* lds, const Gemm g, const StaticOrder& S, const Epi& E) {
;     ...
;         const bool has_next = S.next(ui + 1, nxt);
;         const char* nA = has_next ? PG8_APTR(nxt) : cA; const char* nB = has_next ? PG8_BPTR(nxt) : cB;
;         for (int t = 0; t < nt; t += 2) {
;             const bool last = (t == nt - 2);
;             const char* a1 = cA + (size_t)(t + 1) * kstep;
;             const char* a2 = last ? nA : cA + (size_t)(t + 2) * kstep; const char* b2 = last ? nB : cB + (size_t)(t + 2) * kstep;
;             const char* a3 = a2 + kstep; const char* b3 = b2 + kstep;
;     ...
; #pragma unroll
;         for (int a = 0; a < 2; ++a)
; #pragma unroll
;             for (int b = 0; b < 2; ++b)
; #pragma unroll
;                 for (int m = 0; m < 4; ++m)
; #pragma unroll
;                     for (int n = 0; n < 2; ++n) acc[a][b][m][n] = (f32x4){0.f, 0.f, 0.f, 0.f}; }
.LBB0_190:
	s_ashr_i32 s15, s14, 31
	s_lshl_b64 s[16:17], s[14:15], 20
	s_add_u32 s16, s56, s16
	s_addc_u32 s17, s57, s17
	s_and_b64 s[18:19], s[6:7], exec
	s_cselect_b32 s15, s17, s21
	s_cselect_b32 s39, s16, s20
	s_ashr_i32 s13, s12, 31
	s_lshl_b64 s[18:19], s[12:13], 20
	s_add_u32 s18, s60, s18
	s_addc_u32 s19, s61, s19
	s_and_b64 s[24:25], s[6:7], exec
	s_cselect_b32 s13, s19, s23
	s_cselect_b32 s40, s18, s22
	s_add_u32 s20, s20, 0x80080
	s_addc_u32 s21, s21, 0
	s_add_u32 s41, s22, 0x100
	v_mov_b32_e32 v4, 0
	s_addc_u32 s44, s23, 0
	s_mov_b32 s45, -2
	v_mov_b32_e32 v5, v4
	v_mov_b64_e32 v[6:7], 0
	v_mov_b64_e32 v[8:9], 0
	v_mov_b64_e32 v[10:11], 0
	v_mov_b64_e32 v[12:13], 0
	v_mov_b64_e32 v[14:15], 0
	v_mov_b64_e32 v[16:17], 0
	v_mov_b64_e32 v[18:19], 0
	v_mov_b64_e32 v[20:21], 0
	v_mov_b64_e32 v[22:23], 0
	v_mov_b64_e32 v[24:25], 0
	v_mov_b64_e32 v[26:27], 0
	v_mov_b64_e32 v[28:29], 0
	v_mov_b64_e32 v[30:31], 0
	v_mov_b64_e32 v[32:33], 0
	v_mov_b64_e32 v[34:35], 0
	v_mov_b64_e32 v[36:37], 0
	v_mov_b64_e32 v[38:39], 0
	v_mov_b64_e32 v[40:41], 0
	v_mov_b64_e32 v[42:43], 0
	v_mov_b64_e32 v[44:45], 0
	v_mov_b64_e32 v[46:47], 0
	v_mov_b64_e32 v[48:49], 0
	v_mov_b64_e32 v[50:51], 0
	v_mov_b64_e32 v[52:53], 0
	v_mov_b64_e32 v[54:55], 0
	v_mov_b64_e32 v[56:57], 0
	v_mov_b64_e32 v[58:59], 0
	v_mov_b64_e32 v[60:61], 0
	v_mov_b64_e32 v[62:63], 0
	v_mov_b64_e32 v[64:65], 0
	v_mov_b64_e32 v[66:67], 0
	v_mov_b64_e32 v[68:69], 0
	v_mov_b64_e32 v[70:71], 0
	v_mov_b64_e32 v[72:73], 0
	v_mov_b64_e32 v[74:75], 0
	v_mov_b64_e32 v[76:77], 0
	v_mov_b64_e32 v[78:79], 0
	v_mov_b64_e32 v[80:81], 0
	v_mov_b64_e32 v[82:83], 0
	v_mov_b64_e32 v[84:85], 0
	v_mov_b64_e32 v[86:87], 0
	v_mov_b64_e32 v[88:89], 0
	v_mov_b64_e32 v[90:91], 0
	v_mov_b64_e32 v[92:93], 0
	v_mov_b64_e32 v[94:95], 0
	v_mov_b64_e32 v[96:97], 0
	v_mov_b64_e32 v[98:99], 0
	v_mov_b64_e32 v[100:101], 0
	v_mov_b64_e32 v[102:103], 0
	v_mov_b64_e32 v[104:105], 0
	v_mov_b64_e32 v[106:107], 0
	v_mov_b64_e32 v[108:109], 0
	v_mov_b64_e32 v[110:111], 0
	v_mov_b64_e32 v[112:113], 0
	v_mov_b64_e32 v[114:115], 0
	v_mov_b64_e32 v[116:117], 0
	v_mov_b64_e32 v[118:119], 0
	v_mov_b64_e32 v[120:121], 0
	v_mov_b64_e32 v[122:123], 0
	v_mov_b64_e32 v[124:125], 0
	v_mov_b64_e32 v[126:127], 0
	v_mov_b64_e32 v[128:129], 0
	v_mov_b64_e32 v[130:131], 0

; template <class Epi>
; __device__ __forceinline__ void gemm_phase(LAS unsigned char* lds, const Gemm g, const StaticOrder& S, const Epi& E) {
;     ...
;         const bool has_next = S.next(ui + 1, nxt);
;         const char* nA = has_next ? PG8_APTR(nxt) : cA; const char* nB = has_next ? PG8_BPTR(nxt) : cB;
;         for (int t = 0; t < nt; t += 2) {
;             const bool last = (t == nt - 2);
;             const char* a1 = cA + (size_t)(t + 1) * kstep;
;             const char* a2 = last ? nA : cA + (size_t)(t + 2) * kstep; const char* b2 = last ? nB : cB + (size_t)(t + 2) * kstep;
;             const char* a3 = a2 + kstep; const char* b3 = b2 + kstep;
;     ...
; #pragma unroll
;         for (int a = 0; a < 2; ++a)
; #pragma unroll
;             for (int b = 0; b < 2; ++b)
; #pragma unroll
;                 for (int m = 0; m < 4; ++m)
; #pragma unroll
;                     for (int n = 0; n < 2; ++n) acc[a][b][m][n] = (f32x4){0.f, 0.f, 0.f, 0.f}; }
.LBB0_1740:
	s_ashr_i32 s21, s20, 31
	s_lshl_b64 s[22:23], s[20:21], 20
	s_add_u32 s22, s66, s22
	s_addc_u32 s23, s67, s23
	s_and_b64 s[24:25], s[12:13], exec
	s_cselect_b32 s21, s23, s27
	s_cselect_b32 s74, s22, s26
	s_ashr_i32 s19, s18, 31
	s_lshl_b64 s[24:25], s[18:19], 20
	s_add_u32 s24, s6, s24
	s_addc_u32 s25, s7, s25
	s_and_b64 s[30:31], s[12:13], exec
	s_cselect_b32 s19, s25, s29
	s_cselect_b32 s75, s24, s28
	s_add_u32 s26, s26, 0x80080
	s_addc_u32 s27, s27, 0
	s_add_u32 s76, s28, 0x100
	v_mov_b32_e32 v4, 0
	s_addc_u32 s77, s29, 0
	s_mov_b32 s80, -2
	s_waitcnt lgkmcnt(0)
	v_mov_b32_e32 v5, v4
	v_mov_b64_e32 v[6:7], 0
	v_mov_b64_e32 v[8:9], 0
	v_mov_b64_e32 v[10:11], 0
	v_mov_b64_e32 v[12:13], 0
	v_mov_b64_e32 v[14:15], 0
	v_mov_b64_e32 v[16:17], 0
	v_mov_b64_e32 v[18:19], 0
	v_mov_b64_e32 v[20:21], 0
	v_mov_b64_e32 v[22:23], 0
	v_mov_b64_e32 v[24:25], 0
	v_mov_b64_e32 v[26:27], 0
	v_mov_b64_e32 v[28:29], 0
	v_mov_b64_e32 v[30:31], 0
	v_mov_b64_e32 v[32:33], 0
	v_mov_b64_e32 v[34:35], 0
	v_mov_b64_e32 v[36:37], 0
	v_mov_b64_e32 v[38:39], 0
	v_mov_b64_e32 v[40:41], 0
	v_mov_b64_e32 v[42:43], 0
	v_mov_b64_e32 v[44:45], 0
	v_mov_b64_e32 v[46:47], 0
	v_mov_b64_e32 v[48:49], 0
	v_mov_b64_e32 v[50:51], 0
	v_mov_b64_e32 v[52:53], 0
	v_mov_b64_e32 v[54:55], 0
	v_mov_b64_e32 v[56:57], 0
	v_mov_b64_e32 v[58:59], 0
	v_mov_b64_e32 v[60:61], 0
	v_mov_b64_e32 v[62:63], 0
	v_mov_b64_e32 v[64:65], 0
	v_mov_b64_e32 v[66:67], 0
	v_mov_b64_e32 v[68:69], 0
	v_mov_b64_e32 v[70:71], 0
	v_mov_b64_e32 v[72:73], 0
	v_mov_b64_e32 v[74:75], 0
	v_mov_b64_e32 v[76:77], 0
	v_mov_b64_e32 v[78:79], 0
	v_mov_b64_e32 v[80:81], 0
	v_mov_b64_e32 v[82:83], 0
	v_mov_b64_e32 v[84:85], 0
	v_mov_b64_e32 v[86:87], 0
	v_mov_b64_e32 v[88:89], 0
	v_mov_b64_e32 v[90:91], 0
	v_mov_b64_e32 v[92:93], 0
	v_mov_b64_e32 v[94:95], 0
	v_mov_b64_e32 v[96:97], 0
	v_mov_b64_e32 v[98:99], 0
	v_mov_b64_e32 v[100:101], 0
	v_mov_b64_e32 v[102:103], 0
	v_mov_b64_e32 v[104:105], 0
	v_mov_b64_e32 v[106:107], 0
	v_mov_b64_e32 v[108:109], 0
	v_mov_b64_e32 v[110:111], 0
	v_mov_b64_e32 v[112:113], 0
	v_mov_b64_e32 v[114:115], 0
	v_mov_b64_e32 v[116:117], 0
	v_mov_b64_e32 v[118:119], 0
	v_mov_b64_e32 v[120:121], 0
	v_mov_b64_e32 v[122:123], 0
	v_mov_b64_e32 v[124:125], 0
	v_mov_b64_e32 v[126:127], 0
	v_mov_b64_e32 v[128:129], 0
	v_mov_b64_e32 v[130:131], 0

; template <class Epi>
; __device__ __forceinline__ void gemm_phase(LAS unsigned char* lds, const Gemm g, const StaticOrder& S, const Epi& E) {
;     ...
;         const bool has_next = S.next(ui + 1, nxt);
;         const char* nA = has_next ? PG8_APTR(nxt) : cA; const char* nB = has_next ? PG8_BPTR(nxt) : cB;
;         for (int t = 0; t < nt; t += 2) {
;             const bool last = (t == nt - 2);
;             const char* a1 = cA + (size_t)(t + 1) * kstep;
;             const char* a2 = last ? nA : cA + (size_t)(t + 2) * kstep; const char* b2 = last ? nB : cB + (size_t)(t + 2) * kstep;
;             const char* a3 = a2 + kstep; const char* b3 = b2 + kstep;
;     ...
; #pragma unroll
;         for (int a = 0; a < 2; ++a)
; #pragma unroll
;             for (int b = 0; b < 2; ++b)
; #pragma unroll
;                 for (int m = 0; m < 4; ++m)
; #pragma unroll
;                     for (int n = 0; n < 2; ++n) acc[a][b][m][n] = (f32x4){0.f, 0.f, 0.f, 0.f}; }
.LBB0_1825:
	s_ashr_i32 s19, s18, 31
	s_lshl_b64 s[20:21], s[18:19], 20
	s_add_u32 s20, s56, s20
	s_addc_u32 s21, s57, s21
	s_and_b64 s[22:23], s[10:11], exec
	s_cselect_b32 s19, s21, s25
	s_cselect_b32 s45, s20, s24
	s_ashr_i32 s17, s16, 31
	s_lshl_b64 s[22:23], s[16:17], 20
	s_add_u32 s22, s6, s22
	s_addc_u32 s23, s7, s23
	s_and_b64 s[28:29], s[10:11], exec
	s_cselect_b32 s17, s23, s27
	s_cselect_b32 s55, s22, s26
	s_add_u32 s24, s24, 0x80080
	s_addc_u32 s25, s25, 0
	s_add_u32 s74, s26, 0x100
	v_mov_b32_e32 v4, 0
	s_addc_u32 s75, s27, 0
	s_mov_b32 s76, -2
	v_mov_b32_e32 v5, v4
	v_mov_b64_e32 v[6:7], 0
	v_mov_b64_e32 v[8:9], 0
	v_mov_b64_e32 v[10:11], 0
	v_mov_b64_e32 v[12:13], 0
	v_mov_b64_e32 v[14:15], 0
	v_mov_b64_e32 v[16:17], 0
	v_mov_b64_e32 v[18:19], 0
	v_mov_b64_e32 v[20:21], 0
	v_mov_b64_e32 v[22:23], 0
	v_mov_b64_e32 v[24:25], 0
	v_mov_b64_e32 v[26:27], 0
	v_mov_b64_e32 v[28:29], 0
	v_mov_b64_e32 v[30:31], 0
	v_mov_b64_e32 v[32:33], 0
	v_mov_b64_e32 v[34:35], 0
	v_mov_b64_e32 v[36:37], 0
	v_mov_b64_e32 v[38:39], 0
	v_mov_b64_e32 v[40:41], 0
	v_mov_b64_e32 v[42:43], 0
	v_mov_b64_e32 v[44:45], 0
	v_mov_b64_e32 v[46:47], 0
	v_mov_b64_e32 v[48:49], 0
	v_mov_b64_e32 v[50:51], 0
	v_mov_b64_e32 v[52:53], 0
	v_mov_b64_e32 v[54:55], 0
	v_mov_b64_e32 v[56:57], 0
	v_mov_b64_e32 v[58:59], 0
	v_mov_b64_e32 v[60:61], 0
	v_mov_b64_e32 v[62:63], 0
	v_mov_b64_e32 v[64:65], 0
	v_mov_b64_e32 v[66:67], 0
	v_mov_b64_e32 v[68:69], 0
	v_mov_b64_e32 v[70:71], 0
	v_mov_b64_e32 v[72:73], 0
	v_mov_b64_e32 v[74:75], 0
	v_mov_b64_e32 v[76:77], 0
	v_mov_b64_e32 v[78:79], 0
	v_mov_b64_e32 v[80:81], 0
	v_mov_b64_e32 v[82:83], 0
	v_mov_b64_e32 v[84:85], 0
	v_mov_b64_e32 v[86:87], 0
	v_mov_b64_e32 v[88:89], 0
	v_mov_b64_e32 v[90:91], 0
	v_mov_b64_e32 v[92:93], 0
	v_mov_b64_e32 v[94:95], 0
	v_mov_b64_e32 v[96:97], 0
	v_mov_b64_e32 v[98:99], 0
	v_mov_b64_e32 v[100:101], 0
	v_mov_b64_e32 v[102:103], 0
	v_mov_b64_e32 v[104:105], 0
	v_mov_b64_e32 v[106:107], 0
	v_mov_b64_e32 v[108:109], 0
	v_mov_b64_e32 v[110:111], 0
	v_mov_b64_e32 v[112:113], 0
	v_mov_b64_e32 v[114:115], 0
	v_mov_b64_e32 v[116:117], 0
	v_mov_b64_e32 v[118:119], 0
	v_mov_b64_e32 v[120:121], 0
	v_mov_b64_e32 v[122:123], 0
	v_mov_b64_e32 v[124:125], 0
	v_mov_b64_e32 v[126:127], 0
	v_mov_b64_e32 v[128:129], 0
	v_mov_b64_e32 v[130:131], 0

; template <class Epi>
; __device__ __forceinline__ void gemm_phase(LAS unsigned char* lds, const Gemm g, const StaticOrder& S, const Epi& E) {
;     ...
;         const bool has_next = S.next(ui + 1, nxt);
;         const char* nA = has_next ? PG8_APTR(nxt) : cA; const char* nB = has_next ? PG8_BPTR(nxt) : cB;
;         for (int t = 0; t < nt; t += 2) {
;             const bool last = (t == nt - 2);
;             const char* a1 = cA + (size_t)(t + 1) * kstep;
;             const char* a2 = last ? nA : cA + (size_t)(t + 2) * kstep; const char* b2 = last ? nB : cB + (size_t)(t + 2) * kstep;
;             const char* a3 = a2 + kstep; const char* b3 = b2 + kstep;
;     ...
; #pragma unroll
;         for (int a = 0; a < 2; ++a)
; #pragma unroll
;             for (int b = 0; b < 2; ++b)
; #pragma unroll
;                 for (int m = 0; m < 4; ++m)
; #pragma unroll
;                     for (int n = 0; n < 2; ++n) acc[a][b][m][n] = (f32x4){0.f, 0.f, 0.f, 0.f}; }
.LBB0_1971:
	s_ashr_i32 s17, s16, 31
	s_lshl_b64 s[18:19], s[16:17], 22
	s_add_u32 s18, s64, s18
	s_addc_u32 s19, s65, s19
	s_and_b64 s[20:21], s[10:11], exec
	s_cselect_b32 s17, s19, s23
	s_cselect_b32 s45, s18, s22
	s_ashr_i32 s15, s14, 31
	s_lshl_b64 s[20:21], s[14:15], 22
	s_add_u32 s20, s28, s20
	s_addc_u32 s21, s29, s21
	s_and_b64 s[26:27], s[10:11], exec
	s_cselect_b32 s15, s21, s25
	s_cselect_b32 s55, s20, s24
	s_add_u32 s22, s22, 0x200080
	s_addc_u32 s23, s23, 0
	s_add_u32 s60, s24, 0x100
	v_mov_b32_e32 v4, 0
	s_addc_u32 s61, s25, 0
	s_mov_b32 s74, -2
	s_waitcnt lgkmcnt(0)
	v_mov_b32_e32 v5, v4
	v_mov_b64_e32 v[6:7], 0
	v_mov_b64_e32 v[8:9], 0
	v_mov_b64_e32 v[10:11], 0
	v_mov_b64_e32 v[12:13], 0
	v_mov_b64_e32 v[14:15], 0
	v_mov_b64_e32 v[16:17], 0
	v_mov_b64_e32 v[18:19], 0
	v_mov_b64_e32 v[20:21], 0
	v_mov_b64_e32 v[22:23], 0
	v_mov_b64_e32 v[24:25], 0
	v_mov_b64_e32 v[26:27], 0
	v_mov_b64_e32 v[28:29], 0
	v_mov_b64_e32 v[30:31], 0
	v_mov_b64_e32 v[32:33], 0
	v_mov_b64_e32 v[34:35], 0
	v_mov_b64_e32 v[36:37], 0
	v_mov_b64_e32 v[38:39], 0
	v_mov_b64_e32 v[40:41], 0
	v_mov_b64_e32 v[42:43], 0
	v_mov_b64_e32 v[44:45], 0
	v_mov_b64_e32 v[46:47], 0
	v_mov_b64_e32 v[48:49], 0
	v_mov_b64_e32 v[50:51], 0
	v_mov_b64_e32 v[52:53], 0
	v_mov_b64_e32 v[54:55], 0
	v_mov_b64_e32 v[56:57], 0
	v_mov_b64_e32 v[58:59], 0
	v_mov_b64_e32 v[60:61], 0
	v_mov_b64_e32 v[62:63], 0
	v_mov_b64_e32 v[64:65], 0
	v_mov_b64_e32 v[66:67], 0
	v_mov_b64_e32 v[68:69], 0
	v_mov_b64_e32 v[70:71], 0
	v_mov_b64_e32 v[72:73], 0
	v_mov_b64_e32 v[74:75], 0
	v_mov_b64_e32 v[76:77], 0
	v_mov_b64_e32 v[78:79], 0
	v_mov_b64_e32 v[80:81], 0
	v_mov_b64_e32 v[82:83], 0
	v_mov_b64_e32 v[84:85], 0
	v_mov_b64_e32 v[86:87], 0
	v_mov_b64_e32 v[88:89], 0
	v_mov_b64_e32 v[90:91], 0
	v_mov_b64_e32 v[92:93], 0
	v_mov_b64_e32 v[94:95], 0
	v_mov_b64_e32 v[96:97], 0
	v_mov_b64_e32 v[98:99], 0
	v_mov_b64_e32 v[100:101], 0
	v_mov_b64_e32 v[102:103], 0
	v_mov_b64_e32 v[104:105], 0
	v_mov_b64_e32 v[106:107], 0
	v_mov_b64_e32 v[108:109], 0
	v_mov_b64_e32 v[110:111], 0
	v_mov_b64_e32 v[112:113], 0
	v_mov_b64_e32 v[114:115], 0
	v_mov_b64_e32 v[116:117], 0
	v_mov_b64_e32 v[118:119], 0
	v_mov_b64_e32 v[120:121], 0
	v_mov_b64_e32 v[122:123], 0
	v_mov_b64_e32 v[124:125], 0
	v_mov_b64_e32 v[126:127], 0
	v_mov_b64_e32 v[128:129], 0
	v_mov_b64_e32 v[130:131], 0
